# attention K/V loop: compute body at priority 2, per-iteration conversion and loop-top code at priority 0
# speedup vs baseline: 1.0749x; 1.0040x over previous
.LBB0_430:
	s_setprio 0
	s_add_i32 s55, s50, -1
	s_and_b32 s56, s55, 1
	s_mul_i32 s0, s56, 0x4600
	s_add_i32 s54, s0, 0
	v_mov_b32_e32 v64, v189
	s_cmp_ge_i32 s55, s48
	s_cbranch_scc1 .LBB0_441
	s_add_i32 s0, s51, s53
	s_cmpk_lt_i32 s0, 0x6400
	s_cselect_b32 s57, s0, -1
	s_cmp_lt_i32 s57, 0
	s_cbranch_scc1 .LBB0_441
	s_cmpk_gt_u32 s57, 0x2ff
	s_cbranch_scc0 .LBB0_435
	s_cmpk_gt_u32 s57, 0x3ff
	s_cbranch_scc0 .LBB0_436
	s_add_i32 s0, s57, 0xfffffc00
	s_and_b32 s4, s0, 0xffffe000
	s_cmpk_eq_i32 s4, 0x2000
	s_cselect_b32 s4, s42, 0xb0
	s_cmpk_gt_u32 s0, 0x1fff
	s_cselect_b32 s4, s4, 0xa0
	v_readlane_b32 s26, v255, 2
	v_readlane_b32 s27, v255, 3
	s_add_u32 s4, s26, s4
	s_addc_u32 s5, s27, 0
	s_load_dwordx2 s[4:5], s[4:5], 0x0
	s_lshl_b32 s0, s0, 14
	s_and_b32 s0, s0, 0x7c00000
	s_waitcnt lgkmcnt(0)
	s_add_u32 s4, s4, s0
	s_addc_u32 s5, s5, 0
	s_lshl_b32 s0, s57, 2
	s_and_b32 s58, s0, 0x3c0
	s_lshl_b32 s0, s57, 6
	s_and_b32 s0, s0, 0x3c0
	s_cbranch_execz .LBB0_437
	s_branch .LBB0_438

.LBB0_452:
	s_setprio 2
	v_add3_u32 v64, s54, v190, v215
	ds_read_b128 v[66:69], v64
	ds_read_b128 v[70:73], v64 offset:32
	v_lshl_add_u64 v[136:137], v[198:199], 0, s[16:17]
	v_add_co_u32_e32 v138, vcc, 0xdee2000, v136
	s_waitcnt lgkmcnt(0)
	v_mfma_f32_32x32x16_bf16 v[100:115], v[66:69], v[132:135], 0
	v_addc_co_u32_e32 v139, vcc, 0, v137, vcc
	v_add_co_u32_e32 v140, vcc, 0xdee3000, v136
	s_nop 1
	v_addc_co_u32_e32 v141, vcc, 0, v137, vcc
	v_mfma_f32_32x32x16_bf16 v[84:99], v[66:69], v[172:175], 0
	v_mfma_f32_32x32x16_bf16 v[100:115], v[70:73], v[156:159], v[100:115]
	v_mfma_f32_32x32x16_bf16 v[84:99], v[70:73], v[168:171], v[84:99]
	ds_read_b128 v[66:69], v64 offset:64
	ds_read_b128 v[70:73], v64 offset:96
	ds_read_b128 v[202:205], v64 offset:4640
	s_waitcnt lgkmcnt(0)
	v_mfma_f32_32x32x16_bf16 v[100:115], v[66:69], v[152:155], v[100:115]
	v_mfma_f32_32x32x16_bf16 v[84:99], v[66:69], v[164:167], v[84:99]
	ds_read_b128 v[66:69], v64 offset:4608
	global_load_dwordx4 v[136:139], v[138:139], off
	s_nop 0
	global_load_dwordx4 v[140:143], v[140:141], off
	ds_read_b128 v[206:209], v64 offset:4672
	ds_read_b128 v[218:221], v64 offset:4704
	v_mfma_f32_32x32x16_bf16 v[100:115], v[70:73], v[148:151], v[100:115]
	v_mfma_f32_32x32x16_bf16 v[84:99], v[70:73], v[160:163], v[84:99]
	s_waitcnt lgkmcnt(0)
	v_mfma_f32_32x32x16_bf16 v[116:131], v[66:69], v[132:135], 0
	v_mfma_f32_32x32x16_bf16 v[68:83], v[66:69], v[172:175], 0
	v_lshl_add_u64 v[66:67], v[200:201], 0, s[16:17]
	v_add_co_u32_e32 v144, vcc, 0xe3de000, v66
	s_nop 1
	v_addc_co_u32_e32 v145, vcc, 0, v67, vcc
	v_add_co_u32_e32 v66, vcc, 0xe422000, v66
	v_mfma_f32_32x32x16_bf16 v[116:131], v[202:205], v[156:159], v[116:131]
	s_nop 0
	v_addc_co_u32_e32 v67, vcc, 0, v67, vcc
	global_load_dwordx4 v[176:179], v[144:145], off offset:256
	s_nop 0
	global_load_dwordx4 v[144:147], v[66:67], off offset:256
	v_max_f32_e32 v66, v100, v100
	v_mfma_f32_32x32x16_bf16 v[116:131], v[206:209], v[152:155], v[116:131]
	v_mfma_f32_32x32x16_bf16 v[116:131], v[218:221], v[148:151], v[116:131]
	v_mfma_f32_32x32x16_bf16 v[68:83], v[202:205], v[168:171], v[68:83]
	s_nop 10
	v_max_f32_e32 v64, v116, v116
	v_max_f32_e32 v64, v66, v64
	v_max3_f32 v64, v64, v101, v117
	v_max3_f32 v64, v64, v102, v118
	v_max3_f32 v64, v64, v103, v119
	v_max3_f32 v64, v64, v104, v120
	v_max3_f32 v64, v64, v105, v121
	v_max3_f32 v64, v64, v106, v122
	v_max3_f32 v64, v64, v107, v123
	v_mfma_f32_32x32x16_bf16 v[68:83], v[206:209], v[164:167], v[68:83]
	v_max3_f32 v64, v64, v108, v124
	v_max3_f32 v64, v64, v109, v125
	v_max3_f32 v64, v64, v110, v126
	v_max3_f32 v64, v64, v111, v127
	v_max3_f32 v64, v64, v112, v128
	v_max3_f32 v64, v64, v113, v129
	v_max3_f32 v64, v64, v114, v130
	v_max3_f32 v64, v64, v115, v131
	v_mfma_f32_32x32x16_bf16 v[68:83], v[218:221], v[160:163], v[68:83]
	ds_bpermute_b32 v66, v191, v64
	s_waitcnt lgkmcnt(0)
	v_max3_f32 v66, v216, v64, v66
	v_cmp_gt_f32_e32 vcc, v66, v216
	s_cbranch_vccz .LBB0_454
	v_sub_f32_e32 v64, v216, v66
	v_exp_f32_e32 v64, v64
	s_nop 0
	v_pk_mul_f32 v[62:63], v[62:63], v[64:65] op_sel_hi:[1,0]
	v_pk_mul_f32 v[60:61], v[60:61], v[64:65] op_sel_hi:[1,0]
	v_pk_mul_f32 v[58:59], v[58:59], v[64:65] op_sel_hi:[1,0]
	v_pk_mul_f32 v[56:57], v[56:57], v[64:65] op_sel_hi:[1,0]
	v_pk_mul_f32 v[54:55], v[54:55], v[64:65] op_sel_hi:[1,0]
	v_pk_mul_f32 v[52:53], v[52:53], v[64:65] op_sel_hi:[1,0]
	v_pk_mul_f32 v[50:51], v[50:51], v[64:65] op_sel_hi:[1,0]
	v_pk_mul_f32 v[48:49], v[48:49], v[64:65] op_sel_hi:[1,0]
	v_pk_mul_f32 v[30:31], v[30:31], v[64:65] op_sel_hi:[1,0]
	v_pk_mul_f32 v[28:29], v[28:29], v[64:65] op_sel_hi:[1,0]
	v_pk_mul_f32 v[26:27], v[26:27], v[64:65] op_sel_hi:[1,0]
	v_pk_mul_f32 v[24:25], v[24:25], v[64:65] op_sel_hi:[1,0]
	v_pk_mul_f32 v[22:23], v[22:23], v[64:65] op_sel_hi:[1,0]
	v_pk_mul_f32 v[20:21], v[20:21], v[64:65] op_sel_hi:[1,0]
	v_pk_mul_f32 v[18:19], v[18:19], v[64:65] op_sel_hi:[1,0]
	v_pk_mul_f32 v[16:17], v[16:17], v[64:65] op_sel_hi:[1,0]
	v_mul_f32_e32 v194, v194, v64
	s_branch .LBB0_455

.LBB0_460:
	s_setprio 0
	s_cmpk_lt_i32 s25, 0x43
	s_cbranch_scc1 .LBB0_471
	s_add_i32 s0, s31, 0x42
	s_mul_i32 s0, s0, s33
	v_readlane_b32 s4, v255, 0
	s_add_i32 s0, s0, s4
	s_cmpk_lt_i32 s0, 0x6400
	s_cselect_b32 s49, s0, -1
	s_cmp_lt_i32 s49, 0
	v_readlane_b32 s5, v255, 1
	s_cbranch_scc1 .LBB0_471
	s_cmpk_lt_u32 s49, 0x300
	s_mov_b64 s[26:27], -1
	s_cbranch_scc1 .LBB0_468
	s_cmpk_lt_u32 s49, 0x400
	s_cbranch_scc1 .LBB0_465
	s_add_i32 s0, s49, 0xfffffc00
	s_and_b32 s4, s0, 0xffffe000
	s_cmpk_eq_i32 s4, 0x2000
	s_cselect_b32 s4, s45, 0x8ca0000
	s_cmpk_gt_u32 s0, 0x1fff
	s_cselect_b32 s4, s4, 0xca0000
	s_add_u32 s4, s94, s4
	s_addc_u32 s5, s95, 0
	s_lshl_b32 s0, s0, 13
	s_and_b32 s0, s0, 0x3e00000
	s_add_u32 s4, s4, s0
	s_addc_u32 s5, s5, 0
	s_lshl_b32 s0, s49, 2
	s_lshl_b32 s25, s49, 6
	s_and_b32 s0, s0, 0x3c0
	s_and_b32 s25, s25, 0x3c0
	s_mov_b64 s[26:27], 0
